# GEMM K-loops: all s_setprio flips deleted, no static priority (A/B variant of v5)
# speedup vs baseline: 1.0207x; 1.0083x over previous
.LBB0_147:
	s_or_b64 exec, exec, s[0:1]
	v_readfirstlane_b32 s98, v202
	s_nop 3
	s_lshr_b32 s98, s98, 8
	s_cmp_eq_u32 s98, 1
	s_cbranch_scc0 .Lprio_skip_0
	s_nop 0
